# GEMM-2/GEMM-3 n-chunk order rotated by tile index so co-running blocks read different weight chunks
# speedup vs baseline: 1.0072x; 1.0072x over previous
.Lg2_entry:
	v_and_b32_e32 v200, 63, v208
	v_lshrrev_b32_e32 v201, 6, v208
	v_lshrrev_b32_e32 v202, 3, v200
	v_and_b32_e32 v203, 7, v200
	v_xor_b32_e32 v203, v203, v202
	v_lshlrev_b32_e32 v203, 4, v203
	v_lshl_add_u32 v204, v201, 5, v202
	v_lshl_add_u32 v234, v204, 11, v203
	v_add_u32_e32 v235, 0x4000, v234
	v_add_u32_e32 v236, 0x8000, v234
	v_add_u32_e32 v237, 0xc000, v234
	v_lshlrev_b32_e32 v238, 4, v200
	v_add_u32_e32 v239, 0x8000, v238
	v_add_u32_e32 v240, 0x10000, v238
	v_add_u32_e32 v241, 0x18000, v238
	v_readfirstlane_b32 s8, v201
	s_lshl_b32 s60, s8, 12
	v_and_b32_e32 v200, 63, v208
	v_and_b32_e32 v205, 15, v200
	v_lshrrev_b32_e32 v206, 4, v200
	v_and_b32_e32 v207, 7, v205
	v_xor_b32_e32 v207, v207, v206
	v_lshlrev_b32_e32 v207, 4, v207
	v_lshl_add_u32 v242, v205, 7, v207
	v_xor_b32_e32 v243, 64, v242
	v_mov_b32_e32 v246, 0
	v_mov_b32_e32 v247, 0
	v_mov_b32_e32 v248, 0
	v_mov_b32_e32 v249, 0
	v_mov_b32_e32 v250, 0
	v_mov_b32_e32 v251, 0
	v_mov_b32_e32 v252, 0
	v_mov_b32_e32 v253, 0
	v_readlane_b32 s62, v254, 0
	v_readlane_b32 s63, v254, 1
	s_mov_b32 s21, 0
	s_lshl_b32 s8, s20, 18
	s_add_u32 s52, s92, s8
	s_addc_u32 s53, s93, 0
	s_add_i32 s8, s21, s20
	s_and_b32 s8, s8, 3
	s_lshl_b32 s8, s8, 19
	s_lshl_b32 s24, s60, 5
	s_add_i32 s8, s8, s24
	s_add_i32 s8, s8, 0x34600000
	s_add_u32 s54, s92, s8
	s_addc_u32 s55, s93, 0
	s_mov_b32 s59, 0
	s_mov_b32 s57, 0
	s_add_i32 m0, s57, s60
	s_nop 0
	global_load_lds_dwordx4 v234, s[52:53]
	s_add_i32 m0, m0, 0x400
	s_nop 0
	global_load_lds_dwordx4 v235, s[52:53]
	s_add_i32 m0, m0, 0x400
	s_nop 0
	global_load_lds_dwordx4 v236, s[52:53]
	s_add_i32 m0, m0, 0x400
	s_nop 0
	global_load_lds_dwordx4 v237, s[52:53]
	s_add_u32 s52, s52, 128
	s_addc_u32 s53, s53, 0
	global_load_dwordx4 v[128:131], v238, s[54:55]
	global_load_dwordx4 v[132:135], v239, s[54:55]
	global_load_dwordx4 v[136:139], v240, s[54:55]
	global_load_dwordx4 v[140:143], v241, s[54:55]
	s_add_u32 s54, s54, 1024
	s_addc_u32 s55, s55, 0
	s_add_i32 s59, s59, 1
	global_load_dwordx4 v[144:147], v238, s[54:55]
	global_load_dwordx4 v[148:151], v239, s[54:55]
	global_load_dwordx4 v[152:155], v240, s[54:55]
	global_load_dwordx4 v[156:159], v241, s[54:55]
	s_add_u32 s54, s54, 1024
	s_addc_u32 s55, s55, 0
	s_add_i32 s59, s59, 1
	s_movk_i32 s57, 0x4000
	s_add_i32 m0, s57, s60
	s_nop 0
	global_load_lds_dwordx4 v234, s[52:53]
	s_add_i32 m0, m0, 0x400
	s_nop 0
	global_load_lds_dwordx4 v235, s[52:53]
	s_add_i32 m0, m0, 0x400
	s_nop 0
	global_load_lds_dwordx4 v236, s[52:53]
	s_add_i32 m0, m0, 0x400
	s_nop 0
	global_load_lds_dwordx4 v237, s[52:53]
	s_add_u32 s52, s52, 128
	s_addc_u32 s53, s53, 0
	global_load_dwordx4 v[160:163], v238, s[54:55]
	global_load_dwordx4 v[164:167], v239, s[54:55]
	global_load_dwordx4 v[168:171], v240, s[54:55]
	global_load_dwordx4 v[172:175], v241, s[54:55]
	s_add_u32 s54, s54, 1024
	s_addc_u32 s55, s55, 0
	s_add_i32 s59, s59, 1
	s_mov_b32 s56, 0
	s_mov_b32 s57, 0x8000

.Lg2_sww0:
	s_cmp_lt_u32 s21, 3
	s_cbranch_scc0 .Lg2_wndw0
	s_add_i32 s25, s21, 1
	s_add_i32 s8, s25, s20
	s_and_b32 s8, s8, 3
	s_lshl_b32 s8, s8, 19
	s_lshl_b32 s24, s60, 5
	s_add_i32 s8, s8, s24
	s_add_i32 s8, s8, 0x34600000
	s_add_u32 s54, s92, s8
	s_addc_u32 s55, s93, 0

.Lg2_wndw5:
.Lg2_swdw5:
	s_add_i32 s59, s59, 1
	ds_read_b128 v[200:203], v245 offset:0
	ds_read_b128 v[204:207], v245 offset:2048
	ds_read_b128 v[210:213], v245 offset:4096
	ds_read_b128 v[214:217], v245 offset:6144
	ds_read_b128 v[218:221], v245 offset:8192
	ds_read_b128 v[222:225], v245 offset:10240
	ds_read_b128 v[226:229], v245 offset:12288
	ds_read_b128 v[230:233], v245 offset:14336
	s_waitcnt lgkmcnt(4)
	v_mfma_f32_16x16x32_bf16 v[0:3], v[176:179], v[200:203], v[0:3]
	v_mfma_f32_16x16x32_bf16 v[32:35], v[184:187], v[200:203], v[32:35]
	v_mfma_f32_16x16x32_bf16 v[64:67], v[188:191], v[200:203], v[64:67]
	v_mfma_f32_16x16x32_bf16 v[96:99], v[196:199], v[200:203], v[96:99]
	v_mfma_f32_16x16x32_bf16 v[4:7], v[176:179], v[204:207], v[4:7]
	v_mfma_f32_16x16x32_bf16 v[36:39], v[184:187], v[204:207], v[36:39]
	v_mfma_f32_16x16x32_bf16 v[68:71], v[188:191], v[204:207], v[68:71]
	v_mfma_f32_16x16x32_bf16 v[100:103], v[196:199], v[204:207], v[100:103]
	v_mfma_f32_16x16x32_bf16 v[8:11], v[176:179], v[210:213], v[8:11]
	v_mfma_f32_16x16x32_bf16 v[40:43], v[184:187], v[210:213], v[40:43]
	v_mfma_f32_16x16x32_bf16 v[72:75], v[188:191], v[210:213], v[72:75]
	v_mfma_f32_16x16x32_bf16 v[104:107], v[196:199], v[210:213], v[104:107]
	v_mfma_f32_16x16x32_bf16 v[12:15], v[176:179], v[214:217], v[12:15]
	v_mfma_f32_16x16x32_bf16 v[44:47], v[184:187], v[214:217], v[44:47]
	v_mfma_f32_16x16x32_bf16 v[76:79], v[188:191], v[214:217], v[76:79]
	v_mfma_f32_16x16x32_bf16 v[108:111], v[196:199], v[214:217], v[108:111]
	s_waitcnt lgkmcnt(0)
	v_mfma_f32_16x16x32_bf16 v[16:19], v[176:179], v[218:221], v[16:19]
	v_mfma_f32_16x16x32_bf16 v[48:51], v[184:187], v[218:221], v[48:51]
	v_mfma_f32_16x16x32_bf16 v[80:83], v[188:191], v[218:221], v[80:83]
	v_mfma_f32_16x16x32_bf16 v[112:115], v[196:199], v[218:221], v[112:115]
	v_mfma_f32_16x16x32_bf16 v[20:23], v[176:179], v[222:225], v[20:23]
	v_mfma_f32_16x16x32_bf16 v[52:55], v[184:187], v[222:225], v[52:55]
	v_mfma_f32_16x16x32_bf16 v[84:87], v[188:191], v[222:225], v[84:87]
	v_mfma_f32_16x16x32_bf16 v[116:119], v[196:199], v[222:225], v[116:119]
	v_mfma_f32_16x16x32_bf16 v[24:27], v[176:179], v[226:229], v[24:27]
	v_mfma_f32_16x16x32_bf16 v[56:59], v[184:187], v[226:229], v[56:59]
	v_mfma_f32_16x16x32_bf16 v[88:91], v[188:191], v[226:229], v[88:91]
	v_mfma_f32_16x16x32_bf16 v[120:123], v[196:199], v[226:229], v[120:123]
	v_mfma_f32_16x16x32_bf16 v[28:31], v[176:179], v[230:233], v[28:31]
	v_mfma_f32_16x16x32_bf16 v[60:63], v[184:187], v[230:233], v[60:63]
	v_mfma_f32_16x16x32_bf16 v[92:95], v[188:191], v[230:233], v[92:95]
	v_mfma_f32_16x16x32_bf16 v[124:127], v[196:199], v[230:233], v[124:127]
	s_add_i32 s56, s56, 0x4000
	s_cmp_lt_u32 s56, 0xc000
	s_cselect_b32 s56, s56, 0
	s_add_i32 s57, s57, 0x4000
	s_cmp_lt_u32 s57, 0xc000
	s_cselect_b32 s57, s57, 0
	s_add_i32 s58, s58, 1
	s_cmp_lt_u32 s58, 16
	s_cbranch_scc1 .Lg2_loop
	s_nop 7
	s_nop 7
	v_and_b32_e32 v200, 63, v208
	v_lshrrev_b32_e32 v201, 6, v208
	v_and_b32_e32 v202, 15, v200
	v_lshrrev_b32_e32 v203, 4, v200
	s_add_i32 s24, s21, s20
	s_and_b32 s24, s24, 3
	s_lshl_b32 s24, s24, 8
	s_lshl_b32 s8, s20, 7
	v_add_u32_e32 v204, s8, v202
	v_lshlrev_b32_e32 v205, 2, v203
	v_lshl_add_u32 v205, v201, 6, v205
	v_add_u32_e32 v205, s24, v205
	v_lshlrev_b32_e32 v206, 12, v204
	v_lshl_add_u32 v206, v205, 2, v206
	v_mov_b32_e32 v245, s63
	v_add_co_u32_e32 v244, vcc, s62, v206
	s_nop 1
	v_addc_co_u32_e32 v245, vcc, 0, v245, vcc
	v_lshlrev_b32_e32 v206, 11, v204
	v_lshl_add_u32 v206, v205, 1, v206
	v_add_u32_e32 v206, 0x1e000000, v206
	v_mov_b32_e32 v243, s93
	v_add_co_u32_e32 v242, vcc, s92, v206
	s_nop 1
	v_addc_co_u32_e32 v243, vcc, 0, v243, vcc
	global_load_dwordx4 v[200:203], v[244:245], off offset:0
	global_load_dwordx4 v[204:207], v[244:245], off offset:64
	global_load_dwordx4 v[210:213], v[244:245], off offset:128
	global_load_dwordx4 v[214:217], v[244:245], off offset:192
	v_add_co_u32_e32 v244, vcc, 0x10000, v244
	s_nop 1
	v_addc_co_u32_e32 v245, vcc, 0, v245, vcc
	global_load_dwordx4 v[218:221], v[244:245], off offset:0
	global_load_dwordx4 v[222:225], v[244:245], off offset:64
	global_load_dwordx4 v[226:229], v[244:245], off offset:128
	global_load_dwordx4 v[230:233], v[244:245], off offset:192
	v_add_co_u32_e32 v244, vcc, 0x10000, v244
	s_nop 1
	v_addc_co_u32_e32 v245, vcc, 0, v245, vcc
	s_waitcnt vmcnt(4)
	v_pk_add_f32 v[200:201], v[200:201], v[0:1]
	v_pk_add_f32 v[202:203], v[202:203], v[2:3]
	v_fmac_f32_e32 v246, v200, v200
	v_fmac_f32_e32 v246, v201, v201
	v_fmac_f32_e32 v246, v202, v202
	v_fmac_f32_e32 v246, v203, v203
	v_cvt_pk_bf16_f32 v200, v200, v201
	v_cvt_pk_bf16_f32 v201, v202, v203
	global_store_dwordx2 v[242:243], v[200:201], off offset:0
	v_pk_add_f32 v[204:205], v[204:205], v[32:33]
	v_pk_add_f32 v[206:207], v[206:207], v[34:35]
	v_fmac_f32_e32 v246, v204, v204
	v_fmac_f32_e32 v246, v205, v205
	v_fmac_f32_e32 v246, v206, v206
	v_fmac_f32_e32 v246, v207, v207
	v_cvt_pk_bf16_f32 v204, v204, v205
	v_cvt_pk_bf16_f32 v205, v206, v207
	global_store_dwordx2 v[242:243], v[204:205], off offset:32
	v_pk_add_f32 v[210:211], v[210:211], v[64:65]
	v_pk_add_f32 v[212:213], v[212:213], v[66:67]
	v_fmac_f32_e32 v246, v210, v210
	v_fmac_f32_e32 v246, v211, v211
	v_fmac_f32_e32 v246, v212, v212
	v_fmac_f32_e32 v246, v213, v213
	v_cvt_pk_bf16_f32 v210, v210, v211
	v_cvt_pk_bf16_f32 v211, v212, v213
	global_store_dwordx2 v[242:243], v[210:211], off offset:64
	v_pk_add_f32 v[214:215], v[214:215], v[96:97]
	v_pk_add_f32 v[216:217], v[216:217], v[98:99]
	v_fmac_f32_e32 v246, v214, v214
	v_fmac_f32_e32 v246, v215, v215
	v_fmac_f32_e32 v246, v216, v216
	v_fmac_f32_e32 v246, v217, v217
	v_cvt_pk_bf16_f32 v214, v214, v215
	v_cvt_pk_bf16_f32 v215, v216, v217
	global_store_dwordx2 v[242:243], v[214:215], off offset:96
	v_add_co_u32_e32 v242, vcc, 0x8000, v242
	s_nop 1
	v_addc_co_u32_e32 v243, vcc, 0, v243, vcc
	global_load_dwordx4 v[200:203], v[244:245], off offset:0
	global_load_dwordx4 v[204:207], v[244:245], off offset:64
	global_load_dwordx4 v[210:213], v[244:245], off offset:128
	global_load_dwordx4 v[214:217], v[244:245], off offset:192
	v_add_co_u32_e32 v244, vcc, 0x10000, v244
	s_nop 1
	v_addc_co_u32_e32 v245, vcc, 0, v245, vcc
	s_waitcnt vmcnt(8)
	v_pk_add_f32 v[218:219], v[218:219], v[4:5]
	v_pk_add_f32 v[220:221], v[220:221], v[6:7]
	v_fmac_f32_e32 v247, v218, v218
	v_fmac_f32_e32 v247, v219, v219
	v_fmac_f32_e32 v247, v220, v220
	v_fmac_f32_e32 v247, v221, v221
	v_cvt_pk_bf16_f32 v218, v218, v219
	v_cvt_pk_bf16_f32 v219, v220, v221
	global_store_dwordx2 v[242:243], v[218:219], off offset:0
	v_pk_add_f32 v[222:223], v[222:223], v[36:37]
	v_pk_add_f32 v[224:225], v[224:225], v[38:39]
	v_fmac_f32_e32 v247, v222, v222
	v_fmac_f32_e32 v247, v223, v223
	v_fmac_f32_e32 v247, v224, v224
	v_fmac_f32_e32 v247, v225, v225
	v_cvt_pk_bf16_f32 v222, v222, v223
	v_cvt_pk_bf16_f32 v223, v224, v225
	global_store_dwordx2 v[242:243], v[222:223], off offset:32
	v_pk_add_f32 v[226:227], v[226:227], v[68:69]
	v_pk_add_f32 v[228:229], v[228:229], v[70:71]
	v_fmac_f32_e32 v247, v226, v226
	v_fmac_f32_e32 v247, v227, v227
	v_fmac_f32_e32 v247, v228, v228
	v_fmac_f32_e32 v247, v229, v229
	v_cvt_pk_bf16_f32 v226, v226, v227
	v_cvt_pk_bf16_f32 v227, v228, v229
	global_store_dwordx2 v[242:243], v[226:227], off offset:64
	v_pk_add_f32 v[230:231], v[230:231], v[100:101]
	v_pk_add_f32 v[232:233], v[232:233], v[102:103]
	v_fmac_f32_e32 v247, v230, v230
	v_fmac_f32_e32 v247, v231, v231
	v_fmac_f32_e32 v247, v232, v232
	v_fmac_f32_e32 v247, v233, v233
	v_cvt_pk_bf16_f32 v230, v230, v231
	v_cvt_pk_bf16_f32 v231, v232, v233
	global_store_dwordx2 v[242:243], v[230:231], off offset:96
	v_add_co_u32_e32 v242, vcc, 0x8000, v242
	s_nop 1
	v_addc_co_u32_e32 v243, vcc, 0, v243, vcc
	global_load_dwordx4 v[218:221], v[244:245], off offset:0
	global_load_dwordx4 v[222:225], v[244:245], off offset:64
	global_load_dwordx4 v[226:229], v[244:245], off offset:128
	global_load_dwordx4 v[230:233], v[244:245], off offset:192
	v_add_co_u32_e32 v244, vcc, 0x10000, v244
	s_nop 1
	v_addc_co_u32_e32 v245, vcc, 0, v245, vcc
	s_waitcnt vmcnt(8)
	v_pk_add_f32 v[200:201], v[200:201], v[8:9]
	v_pk_add_f32 v[202:203], v[202:203], v[10:11]
	v_fmac_f32_e32 v248, v200, v200
	v_fmac_f32_e32 v248, v201, v201
	v_fmac_f32_e32 v248, v202, v202
	v_fmac_f32_e32 v248, v203, v203
	v_cvt_pk_bf16_f32 v200, v200, v201
	v_cvt_pk_bf16_f32 v201, v202, v203
	global_store_dwordx2 v[242:243], v[200:201], off offset:0
	v_pk_add_f32 v[204:205], v[204:205], v[40:41]
	v_pk_add_f32 v[206:207], v[206:207], v[42:43]
	v_fmac_f32_e32 v248, v204, v204
	v_fmac_f32_e32 v248, v205, v205
	v_fmac_f32_e32 v248, v206, v206
	v_fmac_f32_e32 v248, v207, v207
	v_cvt_pk_bf16_f32 v204, v204, v205
	v_cvt_pk_bf16_f32 v205, v206, v207
	global_store_dwordx2 v[242:243], v[204:205], off offset:32
	v_pk_add_f32 v[210:211], v[210:211], v[72:73]
	v_pk_add_f32 v[212:213], v[212:213], v[74:75]
	v_fmac_f32_e32 v248, v210, v210
	v_fmac_f32_e32 v248, v211, v211
	v_fmac_f32_e32 v248, v212, v212
	v_fmac_f32_e32 v248, v213, v213
	v_cvt_pk_bf16_f32 v210, v210, v211
	v_cvt_pk_bf16_f32 v211, v212, v213
	global_store_dwordx2 v[242:243], v[210:211], off offset:64
	v_pk_add_f32 v[214:215], v[214:215], v[104:105]
	v_pk_add_f32 v[216:217], v[216:217], v[106:107]
	v_fmac_f32_e32 v248, v214, v214
	v_fmac_f32_e32 v248, v215, v215
	v_fmac_f32_e32 v248, v216, v216
	v_fmac_f32_e32 v248, v217, v217
	v_cvt_pk_bf16_f32 v214, v214, v215
	v_cvt_pk_bf16_f32 v215, v216, v217
	global_store_dwordx2 v[242:243], v[214:215], off offset:96
	v_add_co_u32_e32 v242, vcc, 0x8000, v242
	s_nop 1
	v_addc_co_u32_e32 v243, vcc, 0, v243, vcc
	global_load_dwordx4 v[200:203], v[244:245], off offset:0
	global_load_dwordx4 v[204:207], v[244:245], off offset:64
	global_load_dwordx4 v[210:213], v[244:245], off offset:128
	global_load_dwordx4 v[214:217], v[244:245], off offset:192
	v_add_co_u32_e32 v244, vcc, 0x10000, v244
	s_nop 1
	v_addc_co_u32_e32 v245, vcc, 0, v245, vcc
	s_waitcnt vmcnt(8)
	v_pk_add_f32 v[218:219], v[218:219], v[12:13]
	v_pk_add_f32 v[220:221], v[220:221], v[14:15]
	v_fmac_f32_e32 v249, v218, v218
	v_fmac_f32_e32 v249, v219, v219
	v_fmac_f32_e32 v249, v220, v220
	v_fmac_f32_e32 v249, v221, v221
	v_cvt_pk_bf16_f32 v218, v218, v219
	v_cvt_pk_bf16_f32 v219, v220, v221
	global_store_dwordx2 v[242:243], v[218:219], off offset:0
	v_pk_add_f32 v[222:223], v[222:223], v[44:45]
	v_pk_add_f32 v[224:225], v[224:225], v[46:47]
	v_fmac_f32_e32 v249, v222, v222
	v_fmac_f32_e32 v249, v223, v223
	v_fmac_f32_e32 v249, v224, v224
	v_fmac_f32_e32 v249, v225, v225
	v_cvt_pk_bf16_f32 v222, v222, v223
	v_cvt_pk_bf16_f32 v223, v224, v225
	global_store_dwordx2 v[242:243], v[222:223], off offset:32
	v_pk_add_f32 v[226:227], v[226:227], v[76:77]
	v_pk_add_f32 v[228:229], v[228:229], v[78:79]
	v_fmac_f32_e32 v249, v226, v226
	v_fmac_f32_e32 v249, v227, v227
	v_fmac_f32_e32 v249, v228, v228
	v_fmac_f32_e32 v249, v229, v229
	v_cvt_pk_bf16_f32 v226, v226, v227
	v_cvt_pk_bf16_f32 v227, v228, v229
	global_store_dwordx2 v[242:243], v[226:227], off offset:64
	v_pk_add_f32 v[230:231], v[230:231], v[108:109]
	v_pk_add_f32 v[232:233], v[232:233], v[110:111]
	v_fmac_f32_e32 v249, v230, v230
	v_fmac_f32_e32 v249, v231, v231
	v_fmac_f32_e32 v249, v232, v232
	v_fmac_f32_e32 v249, v233, v233
	v_cvt_pk_bf16_f32 v230, v230, v231
	v_cvt_pk_bf16_f32 v231, v232, v233
	global_store_dwordx2 v[242:243], v[230:231], off offset:96
	v_add_co_u32_e32 v242, vcc, 0x8000, v242
	s_nop 1
	v_addc_co_u32_e32 v243, vcc, 0, v243, vcc
	global_load_dwordx4 v[218:221], v[244:245], off offset:0
	global_load_dwordx4 v[222:225], v[244:245], off offset:64
	global_load_dwordx4 v[226:229], v[244:245], off offset:128
	global_load_dwordx4 v[230:233], v[244:245], off offset:192
	v_add_co_u32_e32 v244, vcc, 0x10000, v244
	s_nop 1
	v_addc_co_u32_e32 v245, vcc, 0, v245, vcc
	s_waitcnt vmcnt(8)
	v_pk_add_f32 v[200:201], v[200:201], v[16:17]
	v_pk_add_f32 v[202:203], v[202:203], v[18:19]
	v_fmac_f32_e32 v250, v200, v200
	v_fmac_f32_e32 v250, v201, v201
	v_fmac_f32_e32 v250, v202, v202
	v_fmac_f32_e32 v250, v203, v203
	v_cvt_pk_bf16_f32 v200, v200, v201
	v_cvt_pk_bf16_f32 v201, v202, v203
	global_store_dwordx2 v[242:243], v[200:201], off offset:0
	v_pk_add_f32 v[204:205], v[204:205], v[48:49]
	v_pk_add_f32 v[206:207], v[206:207], v[50:51]
	v_fmac_f32_e32 v250, v204, v204
	v_fmac_f32_e32 v250, v205, v205
	v_fmac_f32_e32 v250, v206, v206
	v_fmac_f32_e32 v250, v207, v207
	v_cvt_pk_bf16_f32 v204, v204, v205
	v_cvt_pk_bf16_f32 v205, v206, v207
	global_store_dwordx2 v[242:243], v[204:205], off offset:32
	v_pk_add_f32 v[210:211], v[210:211], v[80:81]
	v_pk_add_f32 v[212:213], v[212:213], v[82:83]
	v_fmac_f32_e32 v250, v210, v210
	v_fmac_f32_e32 v250, v211, v211
	v_fmac_f32_e32 v250, v212, v212
	v_fmac_f32_e32 v250, v213, v213
	v_cvt_pk_bf16_f32 v210, v210, v211
	v_cvt_pk_bf16_f32 v211, v212, v213
	global_store_dwordx2 v[242:243], v[210:211], off offset:64
	v_pk_add_f32 v[214:215], v[214:215], v[112:113]
	v_pk_add_f32 v[216:217], v[216:217], v[114:115]
	v_fmac_f32_e32 v250, v214, v214
	v_fmac_f32_e32 v250, v215, v215
	v_fmac_f32_e32 v250, v216, v216
	v_fmac_f32_e32 v250, v217, v217
	v_cvt_pk_bf16_f32 v214, v214, v215
	v_cvt_pk_bf16_f32 v215, v216, v217
	global_store_dwordx2 v[242:243], v[214:215], off offset:96
	v_add_co_u32_e32 v242, vcc, 0x8000, v242
	s_nop 1
	v_addc_co_u32_e32 v243, vcc, 0, v243, vcc
	global_load_dwordx4 v[200:203], v[244:245], off offset:0
	global_load_dwordx4 v[204:207], v[244:245], off offset:64
	global_load_dwordx4 v[210:213], v[244:245], off offset:128
	global_load_dwordx4 v[214:217], v[244:245], off offset:192
	v_add_co_u32_e32 v244, vcc, 0x10000, v244
	s_nop 1
	v_addc_co_u32_e32 v245, vcc, 0, v245, vcc
	s_waitcnt vmcnt(8)
	v_pk_add_f32 v[218:219], v[218:219], v[20:21]
	v_pk_add_f32 v[220:221], v[220:221], v[22:23]
	v_fmac_f32_e32 v251, v218, v218
	v_fmac_f32_e32 v251, v219, v219
	v_fmac_f32_e32 v251, v220, v220
	v_fmac_f32_e32 v251, v221, v221
	v_cvt_pk_bf16_f32 v218, v218, v219
	v_cvt_pk_bf16_f32 v219, v220, v221
	global_store_dwordx2 v[242:243], v[218:219], off offset:0
	v_pk_add_f32 v[222:223], v[222:223], v[52:53]
	v_pk_add_f32 v[224:225], v[224:225], v[54:55]
	v_fmac_f32_e32 v251, v222, v222
	v_fmac_f32_e32 v251, v223, v223
	v_fmac_f32_e32 v251, v224, v224
	v_fmac_f32_e32 v251, v225, v225
	v_cvt_pk_bf16_f32 v222, v222, v223
	v_cvt_pk_bf16_f32 v223, v224, v225
	global_store_dwordx2 v[242:243], v[222:223], off offset:32
	v_pk_add_f32 v[226:227], v[226:227], v[84:85]
	v_pk_add_f32 v[228:229], v[228:229], v[86:87]
	v_fmac_f32_e32 v251, v226, v226
	v_fmac_f32_e32 v251, v227, v227
	v_fmac_f32_e32 v251, v228, v228
	v_fmac_f32_e32 v251, v229, v229
	v_cvt_pk_bf16_f32 v226, v226, v227
	v_cvt_pk_bf16_f32 v227, v228, v229
	global_store_dwordx2 v[242:243], v[226:227], off offset:64
	v_pk_add_f32 v[230:231], v[230:231], v[116:117]
	v_pk_add_f32 v[232:233], v[232:233], v[118:119]
	v_fmac_f32_e32 v251, v230, v230
	v_fmac_f32_e32 v251, v231, v231
	v_fmac_f32_e32 v251, v232, v232
	v_fmac_f32_e32 v251, v233, v233
	v_cvt_pk_bf16_f32 v230, v230, v231
	v_cvt_pk_bf16_f32 v231, v232, v233
	global_store_dwordx2 v[242:243], v[230:231], off offset:96
	v_add_co_u32_e32 v242, vcc, 0x8000, v242
	s_nop 1
	v_addc_co_u32_e32 v243, vcc, 0, v243, vcc
	global_load_dwordx4 v[218:221], v[244:245], off offset:0
	global_load_dwordx4 v[222:225], v[244:245], off offset:64
	global_load_dwordx4 v[226:229], v[244:245], off offset:128
	global_load_dwordx4 v[230:233], v[244:245], off offset:192
	v_add_co_u32_e32 v244, vcc, 0x10000, v244
	s_nop 1
	v_addc_co_u32_e32 v245, vcc, 0, v245, vcc
	s_waitcnt vmcnt(8)
	v_pk_add_f32 v[200:201], v[200:201], v[24:25]
	v_pk_add_f32 v[202:203], v[202:203], v[26:27]
	v_fmac_f32_e32 v252, v200, v200
	v_fmac_f32_e32 v252, v201, v201
	v_fmac_f32_e32 v252, v202, v202
	v_fmac_f32_e32 v252, v203, v203
	v_cvt_pk_bf16_f32 v200, v200, v201
	v_cvt_pk_bf16_f32 v201, v202, v203
	global_store_dwordx2 v[242:243], v[200:201], off offset:0
	v_pk_add_f32 v[204:205], v[204:205], v[56:57]
	v_pk_add_f32 v[206:207], v[206:207], v[58:59]
	v_fmac_f32_e32 v252, v204, v204
	v_fmac_f32_e32 v252, v205, v205
	v_fmac_f32_e32 v252, v206, v206
	v_fmac_f32_e32 v252, v207, v207
	v_cvt_pk_bf16_f32 v204, v204, v205
	v_cvt_pk_bf16_f32 v205, v206, v207
	global_store_dwordx2 v[242:243], v[204:205], off offset:32
	v_pk_add_f32 v[210:211], v[210:211], v[88:89]
	v_pk_add_f32 v[212:213], v[212:213], v[90:91]
	v_fmac_f32_e32 v252, v210, v210
	v_fmac_f32_e32 v252, v211, v211
	v_fmac_f32_e32 v252, v212, v212
	v_fmac_f32_e32 v252, v213, v213
	v_cvt_pk_bf16_f32 v210, v210, v211
	v_cvt_pk_bf16_f32 v211, v212, v213
	global_store_dwordx2 v[242:243], v[210:211], off offset:64
	v_pk_add_f32 v[214:215], v[214:215], v[120:121]
	v_pk_add_f32 v[216:217], v[216:217], v[122:123]
	v_fmac_f32_e32 v252, v214, v214
	v_fmac_f32_e32 v252, v215, v215
	v_fmac_f32_e32 v252, v216, v216
	v_fmac_f32_e32 v252, v217, v217
	v_cvt_pk_bf16_f32 v214, v214, v215
	v_cvt_pk_bf16_f32 v215, v216, v217
	global_store_dwordx2 v[242:243], v[214:215], off offset:96
	v_add_co_u32_e32 v242, vcc, 0x8000, v242
	s_nop 1
	v_addc_co_u32_e32 v243, vcc, 0, v243, vcc
	s_waitcnt vmcnt(4)
	v_pk_add_f32 v[218:219], v[218:219], v[28:29]
	v_pk_add_f32 v[220:221], v[220:221], v[30:31]
	v_fmac_f32_e32 v253, v218, v218
	v_fmac_f32_e32 v253, v219, v219
	v_fmac_f32_e32 v253, v220, v220
	v_fmac_f32_e32 v253, v221, v221
	v_cvt_pk_bf16_f32 v218, v218, v219
	v_cvt_pk_bf16_f32 v219, v220, v221
	global_store_dwordx2 v[242:243], v[218:219], off offset:0
	v_pk_add_f32 v[222:223], v[222:223], v[60:61]
	v_pk_add_f32 v[224:225], v[224:225], v[62:63]
	v_fmac_f32_e32 v253, v222, v222
	v_fmac_f32_e32 v253, v223, v223
	v_fmac_f32_e32 v253, v224, v224
	v_fmac_f32_e32 v253, v225, v225
	v_cvt_pk_bf16_f32 v222, v222, v223
	v_cvt_pk_bf16_f32 v223, v224, v225
	global_store_dwordx2 v[242:243], v[222:223], off offset:32
	v_pk_add_f32 v[226:227], v[226:227], v[92:93]
	v_pk_add_f32 v[228:229], v[228:229], v[94:95]
	v_fmac_f32_e32 v253, v226, v226
	v_fmac_f32_e32 v253, v227, v227
	v_fmac_f32_e32 v253, v228, v228
	v_fmac_f32_e32 v253, v229, v229
	v_cvt_pk_bf16_f32 v226, v226, v227
	v_cvt_pk_bf16_f32 v227, v228, v229
	global_store_dwordx2 v[242:243], v[226:227], off offset:64
	v_pk_add_f32 v[230:231], v[230:231], v[124:125]
	v_pk_add_f32 v[232:233], v[232:233], v[126:127]
	v_fmac_f32_e32 v253, v230, v230
	v_fmac_f32_e32 v253, v231, v231
	v_fmac_f32_e32 v253, v232, v232
	v_fmac_f32_e32 v253, v233, v233
	v_cvt_pk_bf16_f32 v230, v230, v231
	v_cvt_pk_bf16_f32 v231, v232, v233
	global_store_dwordx2 v[242:243], v[230:231], off offset:96
	v_add_co_u32_e32 v242, vcc, 0x8000, v242
	s_nop 1
	v_addc_co_u32_e32 v243, vcc, 0, v243, vcc
	v_and_b32_e32 v200, 63, v208
	v_and_b32_e32 v205, 15, v200
	v_lshrrev_b32_e32 v206, 4, v200
	v_and_b32_e32 v207, 7, v205
	v_xor_b32_e32 v207, v207, v206
	v_lshlrev_b32_e32 v207, 4, v207
	v_lshl_add_u32 v242, v205, 7, v207
	v_xor_b32_e32 v243, 64, v242
	s_add_i32 s21, s21, 1
	s_cmp_lt_u32 s21, 4
	s_cbranch_scc1 .Lg2_chunk
	s_waitcnt vmcnt(0)
	v_and_b32_e32 v200, 63, v208
	v_xor_b32_e32 v201, 16, v200
	v_lshlrev_b32_e32 v201, 2, v201
	v_xor_b32_e32 v202, 32, v200
	v_lshlrev_b32_e32 v202, 2, v202
	v_and_b32_e32 v203, 15, v200
	v_lshlrev_b32_e32 v203, 2, v203
	v_add_u32_e32 v203, 0x12400, v203
	ds_bpermute_b32 v204, v201, v246
	s_waitcnt lgkmcnt(0)
	v_add_f32_e32 v246, v246, v204
	ds_bpermute_b32 v204, v202, v246
	s_waitcnt lgkmcnt(0)
	v_add_f32_e32 v246, v246, v204
	ds_bpermute_b32 v204, v201, v247
	s_waitcnt lgkmcnt(0)
	v_add_f32_e32 v247, v247, v204
	ds_bpermute_b32 v204, v202, v247
	s_waitcnt lgkmcnt(0)
	v_add_f32_e32 v247, v247, v204
	ds_bpermute_b32 v204, v201, v248
	s_waitcnt lgkmcnt(0)
	v_add_f32_e32 v248, v248, v204
	ds_bpermute_b32 v204, v202, v248
	s_waitcnt lgkmcnt(0)
	v_add_f32_e32 v248, v248, v204
	ds_bpermute_b32 v204, v201, v249
	s_waitcnt lgkmcnt(0)
	v_add_f32_e32 v249, v249, v204
	ds_bpermute_b32 v204, v202, v249
	s_waitcnt lgkmcnt(0)
	v_add_f32_e32 v249, v249, v204
	ds_bpermute_b32 v204, v201, v250
	s_waitcnt lgkmcnt(0)
	v_add_f32_e32 v250, v250, v204
	ds_bpermute_b32 v204, v202, v250
	s_waitcnt lgkmcnt(0)
	v_add_f32_e32 v250, v250, v204
	ds_bpermute_b32 v204, v201, v251
	s_waitcnt lgkmcnt(0)
	v_add_f32_e32 v251, v251, v204
	ds_bpermute_b32 v204, v202, v251
	s_waitcnt lgkmcnt(0)
	v_add_f32_e32 v251, v251, v204
	ds_bpermute_b32 v204, v201, v252
	s_waitcnt lgkmcnt(0)
	v_add_f32_e32 v252, v252, v204
	ds_bpermute_b32 v204, v202, v252
	s_waitcnt lgkmcnt(0)
	v_add_f32_e32 v252, v252, v204
	ds_bpermute_b32 v204, v201, v253
	s_waitcnt lgkmcnt(0)
	v_add_f32_e32 v253, v253, v204
	ds_bpermute_b32 v204, v202, v253
	s_waitcnt lgkmcnt(0)
	v_add_f32_e32 v253, v253, v204
	s_mov_b64 s[24:25], exec
	s_mov_b64 exec, 0xffff
	ds_add_f32 v203, v246 offset:0
	ds_add_f32 v203, v247 offset:64
	ds_add_f32 v203, v248 offset:128
	ds_add_f32 v203, v249 offset:192
	ds_add_f32 v203, v250 offset:256
	ds_add_f32 v203, v251 offset:320
	ds_add_f32 v203, v252 offset:384
	ds_add_f32 v203, v253 offset:448
	s_mov_b64 exec, s[24:25]


.LBB0_345:
	v_and_b32_e32 v246, 63, v208
	v_lshrrev_b32_e32 v247, 6, v208
	v_lshrrev_b32_e32 v248, 3, v246
	v_and_b32_e32 v249, 7, v246
	v_xor_b32_e32 v249, v249, v248
	v_lshlrev_b32_e32 v249, 4, v249
	v_lshl_add_u32 v250, v247, 5, v248
	v_lshl_add_u32 v234, v250, 11, v249
	v_add_u32_e32 v235, 0x4000, v234
	v_add_u32_e32 v236, 0x8000, v234
	v_add_u32_e32 v237, 0xc000, v234
	v_lshlrev_b32_e32 v238, 4, v246
	v_add_u32_e32 v239, 0x8000, v238
	v_add_u32_e32 v240, 0x10000, v238
	v_add_u32_e32 v241, 0x18000, v238
	v_readfirstlane_b32 s2, v247
	s_lshl_b32 s20, s2, 12
	v_and_b32_e32 v251, 15, v246
	v_lshrrev_b32_e32 v252, 4, v246
	v_and_b32_e32 v253, 7, v251
	v_xor_b32_e32 v253, v253, v252
	v_lshlrev_b32_e32 v253, 4, v253
	v_lshl_add_u32 v242, v251, 7, v253
	v_xor_b32_e32 v243, 64, v242
	s_mov_b32 s11, 0
	v_and_b32_e32 v244, 15, v208
	v_lshlrev_b32_e32 v244, 2, v244
	s_lshl_b32 s2, s10, 9
	s_add_i32 s2, s2, 0x36c80000
	v_add_u32_e32 v244, s2, v244
	v_mov_b32_e32 v245, s93
	v_add_co_u32_e32 v244, vcc, s92, v244
	s_nop 1
	v_addc_co_u32_e32 v245, vcc, 0, v245, vcc
	global_load_dword v246, v[244:245], off
	global_load_dword v247, v[244:245], off offset:64
	global_load_dword v248, v[244:245], off offset:128
	global_load_dword v249, v[244:245], off offset:192
	global_load_dword v250, v[244:245], off offset:256
	global_load_dword v251, v[244:245], off offset:320
	global_load_dword v252, v[244:245], off offset:384
	global_load_dword v253, v[244:245], off offset:448
	s_lshl_b32 s2, s10, 18
	s_add_i32 s2, s2, 0x1e000000
	s_add_u32 s12, s92, s2
	s_addc_u32 s13, s93, 0
	s_add_i32 s2, s11, s10
	s_and_b32 s2, s2, 3
	s_lshl_b32 s2, s2, 19
	s_lshl_b32 s21, s20, 5
	s_add_i32 s2, s2, s21
	s_add_i32 s2, s2, 0x34800000
	s_add_u32 s14, s92, s2
	s_addc_u32 s15, s93, 0
	s_mov_b32 s19, 0
	s_mov_b32 s17, 0
	s_add_i32 m0, s17, s20
	s_nop 0
	global_load_lds_dwordx4 v234, s[12:13]
	s_add_i32 m0, m0, 0x400
	s_nop 0
	global_load_lds_dwordx4 v235, s[12:13]
	s_add_i32 m0, m0, 0x400
	s_nop 0
	global_load_lds_dwordx4 v236, s[12:13]
	s_add_i32 m0, m0, 0x400
	s_nop 0
	global_load_lds_dwordx4 v237, s[12:13]
	s_add_u32 s12, s12, 128
	s_addc_u32 s13, s13, 0
	global_load_dwordx4 v[128:131], v238, s[14:15]
	global_load_dwordx4 v[132:135], v239, s[14:15]
	global_load_dwordx4 v[136:139], v240, s[14:15]
	global_load_dwordx4 v[140:143], v241, s[14:15]
	s_add_u32 s14, s14, 1024
	s_addc_u32 s15, s15, 0
	s_add_i32 s19, s19, 1
	global_load_dwordx4 v[144:147], v238, s[14:15]
	global_load_dwordx4 v[148:151], v239, s[14:15]
	global_load_dwordx4 v[152:155], v240, s[14:15]
	global_load_dwordx4 v[156:159], v241, s[14:15]
	s_add_u32 s14, s14, 1024
	s_addc_u32 s15, s15, 0
	s_add_i32 s19, s19, 1
	s_movk_i32 s17, 0x4000
	s_add_i32 m0, s17, s20
	s_nop 0
	global_load_lds_dwordx4 v234, s[12:13]
	s_add_i32 m0, m0, 0x400
	s_nop 0
	global_load_lds_dwordx4 v235, s[12:13]
	s_add_i32 m0, m0, 0x400
	s_nop 0
	global_load_lds_dwordx4 v236, s[12:13]
	s_add_i32 m0, m0, 0x400
	s_nop 0
	global_load_lds_dwordx4 v237, s[12:13]
	s_add_u32 s12, s12, 128
	s_addc_u32 s13, s13, 0
	global_load_dwordx4 v[160:163], v238, s[14:15]
	global_load_dwordx4 v[164:167], v239, s[14:15]
	global_load_dwordx4 v[168:171], v240, s[14:15]
	global_load_dwordx4 v[172:175], v241, s[14:15]
	s_add_u32 s14, s14, 1024
	s_addc_u32 s15, s15, 0
	s_add_i32 s19, s19, 1
	s_mov_b32 s16, 0
	s_mov_b32 s17, 0x8000

.Lg3_sww0:
	s_cmp_lt_u32 s11, 3
	s_cbranch_scc1 .Lg3_wsamew0
	s_add_i32 s21, s10, s95
	s_cmpk_gt_i32 s21, 0x1ff
	s_cbranch_scc1 .Lg3_wndw0
	s_and_b32 s2, s21, 3
	s_sub_i32 s21, s21, s2
	s_add_i32 s2, s2, s21
	s_and_b32 s2, s2, 3
	s_lshl_b32 s2, s2, 19
	s_lshl_b32 s21, s20, 5
	s_add_i32 s2, s2, s21
	s_add_i32 s2, s2, 0x34800000
	s_add_u32 s14, s92, s2
	s_addc_u32 s15, s93, 0
	s_branch .Lg3_wndw0
.Lg3_wsamew0:
	s_add_i32 s21, s11, 1
	s_add_i32 s2, s21, s10
	s_and_b32 s2, s2, 3
	s_lshl_b32 s2, s2, 19
	s_lshl_b32 s21, s20, 5
	s_add_i32 s2, s2, s21
	s_add_i32 s2, s2, 0x34800000
	s_add_u32 s14, s92, s2
	s_addc_u32 s15, s93, 0

.Lg3_wndw5:
.Lg3_swdw5:
	s_add_i32 s19, s19, 1
	ds_read_b128 v[198:201], v245 offset:0
	ds_read_b128 v[202:205], v245 offset:2048
	ds_read_b128 v[210:213], v245 offset:4096
	ds_read_b128 v[214:217], v245 offset:6144
	ds_read_b128 v[218:221], v245 offset:8192
	ds_read_b128 v[222:225], v245 offset:10240
	ds_read_b128 v[226:229], v245 offset:12288
	ds_read_b128 v[230:233], v245 offset:14336
	s_waitcnt lgkmcnt(4)
	v_mfma_f32_16x16x32_bf16 v[0:3], v[176:179], v[198:201], v[0:3]
	v_mfma_f32_16x16x32_bf16 v[32:35], v[182:185], v[198:201], v[32:35]
	v_mfma_f32_16x16x32_bf16 v[64:67], v[186:189], v[198:201], v[64:67]
	v_mfma_f32_16x16x32_bf16 v[96:99], v[194:197], v[198:201], v[96:99]
	v_mfma_f32_16x16x32_bf16 v[4:7], v[176:179], v[202:205], v[4:7]
	v_mfma_f32_16x16x32_bf16 v[36:39], v[182:185], v[202:205], v[36:39]
	v_mfma_f32_16x16x32_bf16 v[68:71], v[186:189], v[202:205], v[68:71]
	v_mfma_f32_16x16x32_bf16 v[100:103], v[194:197], v[202:205], v[100:103]
	v_mfma_f32_16x16x32_bf16 v[8:11], v[176:179], v[210:213], v[8:11]
	v_mfma_f32_16x16x32_bf16 v[40:43], v[182:185], v[210:213], v[40:43]
	v_mfma_f32_16x16x32_bf16 v[72:75], v[186:189], v[210:213], v[72:75]
	v_mfma_f32_16x16x32_bf16 v[104:107], v[194:197], v[210:213], v[104:107]
	v_mfma_f32_16x16x32_bf16 v[12:15], v[176:179], v[214:217], v[12:15]
	v_mfma_f32_16x16x32_bf16 v[44:47], v[182:185], v[214:217], v[44:47]
	v_mfma_f32_16x16x32_bf16 v[76:79], v[186:189], v[214:217], v[76:79]
	v_mfma_f32_16x16x32_bf16 v[108:111], v[194:197], v[214:217], v[108:111]
	s_waitcnt lgkmcnt(0)
	v_mfma_f32_16x16x32_bf16 v[16:19], v[176:179], v[218:221], v[16:19]
	v_mfma_f32_16x16x32_bf16 v[48:51], v[182:185], v[218:221], v[48:51]
	v_mfma_f32_16x16x32_bf16 v[80:83], v[186:189], v[218:221], v[80:83]
	v_mfma_f32_16x16x32_bf16 v[112:115], v[194:197], v[218:221], v[112:115]
	v_mfma_f32_16x16x32_bf16 v[20:23], v[176:179], v[222:225], v[20:23]
	v_mfma_f32_16x16x32_bf16 v[52:55], v[182:185], v[222:225], v[52:55]
	v_mfma_f32_16x16x32_bf16 v[84:87], v[186:189], v[222:225], v[84:87]
	v_mfma_f32_16x16x32_bf16 v[116:119], v[194:197], v[222:225], v[116:119]
	v_mfma_f32_16x16x32_bf16 v[24:27], v[176:179], v[226:229], v[24:27]
	v_mfma_f32_16x16x32_bf16 v[56:59], v[182:185], v[226:229], v[56:59]
	v_mfma_f32_16x16x32_bf16 v[88:91], v[186:189], v[226:229], v[88:91]
	v_mfma_f32_16x16x32_bf16 v[120:123], v[194:197], v[226:229], v[120:123]
	v_mfma_f32_16x16x32_bf16 v[28:31], v[176:179], v[230:233], v[28:31]
	v_mfma_f32_16x16x32_bf16 v[60:63], v[182:185], v[230:233], v[60:63]
	v_mfma_f32_16x16x32_bf16 v[92:95], v[186:189], v[230:233], v[92:95]
	v_mfma_f32_16x16x32_bf16 v[124:127], v[194:197], v[230:233], v[124:127]
	s_add_i32 s16, s16, 0x4000
	s_cmp_lt_u32 s16, 0xc000
	s_cselect_b32 s16, s16, 0
	s_add_i32 s17, s17, 0x4000
	s_cmp_lt_u32 s17, 0xc000
	s_cselect_b32 s17, s17, 0
	s_add_i32 s18, s18, 1
	s_cmp_lt_u32 s18, 16
	s_cbranch_scc1 .Lg3_loop
	s_nop 7
	s_nop 7
	v_and_b32_e32 v198, 63, v208
	v_lshrrev_b32_e32 v199, 6, v208
	v_and_b32_e32 v200, 15, v198
	v_lshrrev_b32_e32 v201, 4, v198
	s_add_i32 s21, s11, s10
	s_and_b32 s21, s21, 3
	s_lshl_b32 s21, s21, 9
	s_lshl_b32 s2, s10, 18
	s_add_i32 s2, s2, s21
	s_add_i32 s2, s2, 0x26000000
	v_lshlrev_b32_e32 v244, 11, v200
	v_lshl_add_u32 v244, v199, 7, v244
	v_lshl_add_u32 v244, v201, 3, v244
	v_add_u32_e32 v244, s2, v244
	v_mov_b32_e32 v245, s93
	v_add_co_u32_e32 v244, vcc, s92, v244
	s_nop 1
	v_addc_co_u32_e32 v245, vcc, 0, v245, vcc
	v_mul_f32_e32 v0, v246, v0
	v_mul_f32_e32 v1, v246, v1
	v_mul_f32_e32 v2, v246, v2
	v_mul_f32_e32 v3, v246, v3
	v_cvt_pk_bf16_f32 v202, v0, v1
	v_cvt_pk_bf16_f32 v203, v2, v3
	global_store_dwordx2 v[244:245], v[202:203], off offset:0
	v_mul_f32_e32 v32, v246, v32
	v_mul_f32_e32 v33, v246, v33
	v_mul_f32_e32 v34, v246, v34
	v_mul_f32_e32 v35, v246, v35
	v_cvt_pk_bf16_f32 v204, v32, v33
	v_cvt_pk_bf16_f32 v205, v34, v35
	global_store_dwordx2 v[244:245], v[204:205], off offset:32
	v_mul_f32_e32 v64, v246, v64
	v_mul_f32_e32 v65, v246, v65
	v_mul_f32_e32 v66, v246, v66
	v_mul_f32_e32 v67, v246, v67
	v_cvt_pk_bf16_f32 v210, v64, v65
	v_cvt_pk_bf16_f32 v211, v66, v67
	global_store_dwordx2 v[244:245], v[210:211], off offset:64
	v_mul_f32_e32 v96, v246, v96
	v_mul_f32_e32 v97, v246, v97
	v_mul_f32_e32 v98, v246, v98
	v_mul_f32_e32 v99, v246, v99
	v_cvt_pk_bf16_f32 v212, v96, v97
	v_cvt_pk_bf16_f32 v213, v98, v99
	global_store_dwordx2 v[244:245], v[212:213], off offset:96
	v_add_co_u32_e32 v244, vcc, 0x8000, v244
	s_nop 1
	v_addc_co_u32_e32 v245, vcc, 0, v245, vcc
	v_mul_f32_e32 v4, v247, v4
	v_mul_f32_e32 v5, v247, v5
	v_mul_f32_e32 v6, v247, v6
	v_mul_f32_e32 v7, v247, v7
	v_cvt_pk_bf16_f32 v202, v4, v5
	v_cvt_pk_bf16_f32 v203, v6, v7
	global_store_dwordx2 v[244:245], v[202:203], off offset:0
	v_mul_f32_e32 v36, v247, v36
	v_mul_f32_e32 v37, v247, v37
	v_mul_f32_e32 v38, v247, v38
	v_mul_f32_e32 v39, v247, v39
	v_cvt_pk_bf16_f32 v204, v36, v37
	v_cvt_pk_bf16_f32 v205, v38, v39
	global_store_dwordx2 v[244:245], v[204:205], off offset:32
	v_mul_f32_e32 v68, v247, v68
	v_mul_f32_e32 v69, v247, v69
	v_mul_f32_e32 v70, v247, v70
	v_mul_f32_e32 v71, v247, v71
	v_cvt_pk_bf16_f32 v210, v68, v69
	v_cvt_pk_bf16_f32 v211, v70, v71
	global_store_dwordx2 v[244:245], v[210:211], off offset:64
	v_mul_f32_e32 v100, v247, v100
	v_mul_f32_e32 v101, v247, v101
	v_mul_f32_e32 v102, v247, v102
	v_mul_f32_e32 v103, v247, v103
	v_cvt_pk_bf16_f32 v212, v100, v101
	v_cvt_pk_bf16_f32 v213, v102, v103
	global_store_dwordx2 v[244:245], v[212:213], off offset:96
	v_add_co_u32_e32 v244, vcc, 0x8000, v244
	s_nop 1
	v_addc_co_u32_e32 v245, vcc, 0, v245, vcc
	v_mul_f32_e32 v8, v248, v8
	v_mul_f32_e32 v9, v248, v9
	v_mul_f32_e32 v10, v248, v10
	v_mul_f32_e32 v11, v248, v11
	v_cvt_pk_bf16_f32 v202, v8, v9
	v_cvt_pk_bf16_f32 v203, v10, v11
	global_store_dwordx2 v[244:245], v[202:203], off offset:0
	v_mul_f32_e32 v40, v248, v40
	v_mul_f32_e32 v41, v248, v41
	v_mul_f32_e32 v42, v248, v42
	v_mul_f32_e32 v43, v248, v43
	v_cvt_pk_bf16_f32 v204, v40, v41
	v_cvt_pk_bf16_f32 v205, v42, v43
	global_store_dwordx2 v[244:245], v[204:205], off offset:32
	v_mul_f32_e32 v72, v248, v72
	v_mul_f32_e32 v73, v248, v73
	v_mul_f32_e32 v74, v248, v74
	v_mul_f32_e32 v75, v248, v75
	v_cvt_pk_bf16_f32 v210, v72, v73
	v_cvt_pk_bf16_f32 v211, v74, v75
	global_store_dwordx2 v[244:245], v[210:211], off offset:64
	v_mul_f32_e32 v104, v248, v104
	v_mul_f32_e32 v105, v248, v105
	v_mul_f32_e32 v106, v248, v106
	v_mul_f32_e32 v107, v248, v107
	v_cvt_pk_bf16_f32 v212, v104, v105
	v_cvt_pk_bf16_f32 v213, v106, v107
	global_store_dwordx2 v[244:245], v[212:213], off offset:96
	v_add_co_u32_e32 v244, vcc, 0x8000, v244
	s_nop 1
	v_addc_co_u32_e32 v245, vcc, 0, v245, vcc
	v_mul_f32_e32 v12, v249, v12
	v_mul_f32_e32 v13, v249, v13
	v_mul_f32_e32 v14, v249, v14
	v_mul_f32_e32 v15, v249, v15
	v_cvt_pk_bf16_f32 v202, v12, v13
	v_cvt_pk_bf16_f32 v203, v14, v15
	global_store_dwordx2 v[244:245], v[202:203], off offset:0
	v_mul_f32_e32 v44, v249, v44
	v_mul_f32_e32 v45, v249, v45
	v_mul_f32_e32 v46, v249, v46
	v_mul_f32_e32 v47, v249, v47
	v_cvt_pk_bf16_f32 v204, v44, v45
	v_cvt_pk_bf16_f32 v205, v46, v47
	global_store_dwordx2 v[244:245], v[204:205], off offset:32
	v_mul_f32_e32 v76, v249, v76
	v_mul_f32_e32 v77, v249, v77
	v_mul_f32_e32 v78, v249, v78
	v_mul_f32_e32 v79, v249, v79
	v_cvt_pk_bf16_f32 v210, v76, v77
	v_cvt_pk_bf16_f32 v211, v78, v79
	global_store_dwordx2 v[244:245], v[210:211], off offset:64
	v_mul_f32_e32 v108, v249, v108
	v_mul_f32_e32 v109, v249, v109
	v_mul_f32_e32 v110, v249, v110
	v_mul_f32_e32 v111, v249, v111
	v_cvt_pk_bf16_f32 v212, v108, v109
	v_cvt_pk_bf16_f32 v213, v110, v111
	global_store_dwordx2 v[244:245], v[212:213], off offset:96
	v_add_co_u32_e32 v244, vcc, 0x8000, v244
	s_nop 1
	v_addc_co_u32_e32 v245, vcc, 0, v245, vcc
	v_mul_f32_e32 v16, v250, v16
	v_mul_f32_e32 v17, v250, v17
	v_mul_f32_e32 v18, v250, v18
	v_mul_f32_e32 v19, v250, v19
	v_cvt_pk_bf16_f32 v202, v16, v17
	v_cvt_pk_bf16_f32 v203, v18, v19
	global_store_dwordx2 v[244:245], v[202:203], off offset:0
	v_mul_f32_e32 v48, v250, v48
	v_mul_f32_e32 v49, v250, v49
	v_mul_f32_e32 v50, v250, v50
	v_mul_f32_e32 v51, v250, v51
	v_cvt_pk_bf16_f32 v204, v48, v49
	v_cvt_pk_bf16_f32 v205, v50, v51
	global_store_dwordx2 v[244:245], v[204:205], off offset:32
	v_mul_f32_e32 v80, v250, v80
	v_mul_f32_e32 v81, v250, v81
	v_mul_f32_e32 v82, v250, v82
	v_mul_f32_e32 v83, v250, v83
	v_cvt_pk_bf16_f32 v210, v80, v81
	v_cvt_pk_bf16_f32 v211, v82, v83
	global_store_dwordx2 v[244:245], v[210:211], off offset:64
	v_mul_f32_e32 v112, v250, v112
	v_mul_f32_e32 v113, v250, v113
	v_mul_f32_e32 v114, v250, v114
	v_mul_f32_e32 v115, v250, v115
	v_cvt_pk_bf16_f32 v212, v112, v113
	v_cvt_pk_bf16_f32 v213, v114, v115
	global_store_dwordx2 v[244:245], v[212:213], off offset:96
	v_add_co_u32_e32 v244, vcc, 0x8000, v244
	s_nop 1
	v_addc_co_u32_e32 v245, vcc, 0, v245, vcc
	v_mul_f32_e32 v20, v251, v20
	v_mul_f32_e32 v21, v251, v21
	v_mul_f32_e32 v22, v251, v22
	v_mul_f32_e32 v23, v251, v23
	v_cvt_pk_bf16_f32 v202, v20, v21
	v_cvt_pk_bf16_f32 v203, v22, v23
	global_store_dwordx2 v[244:245], v[202:203], off offset:0
	v_mul_f32_e32 v52, v251, v52
	v_mul_f32_e32 v53, v251, v53
	v_mul_f32_e32 v54, v251, v54
	v_mul_f32_e32 v55, v251, v55
	v_cvt_pk_bf16_f32 v204, v52, v53
	v_cvt_pk_bf16_f32 v205, v54, v55
	global_store_dwordx2 v[244:245], v[204:205], off offset:32
	v_mul_f32_e32 v84, v251, v84
	v_mul_f32_e32 v85, v251, v85
	v_mul_f32_e32 v86, v251, v86
	v_mul_f32_e32 v87, v251, v87
	v_cvt_pk_bf16_f32 v210, v84, v85
	v_cvt_pk_bf16_f32 v211, v86, v87
	global_store_dwordx2 v[244:245], v[210:211], off offset:64
	v_mul_f32_e32 v116, v251, v116
	v_mul_f32_e32 v117, v251, v117
	v_mul_f32_e32 v118, v251, v118
	v_mul_f32_e32 v119, v251, v119
	v_cvt_pk_bf16_f32 v212, v116, v117
	v_cvt_pk_bf16_f32 v213, v118, v119
	global_store_dwordx2 v[244:245], v[212:213], off offset:96
	v_add_co_u32_e32 v244, vcc, 0x8000, v244
	s_nop 1
	v_addc_co_u32_e32 v245, vcc, 0, v245, vcc
	v_mul_f32_e32 v24, v252, v24
	v_mul_f32_e32 v25, v252, v25
	v_mul_f32_e32 v26, v252, v26
	v_mul_f32_e32 v27, v252, v27
	v_cvt_pk_bf16_f32 v202, v24, v25
	v_cvt_pk_bf16_f32 v203, v26, v27
	global_store_dwordx2 v[244:245], v[202:203], off offset:0
	v_mul_f32_e32 v56, v252, v56
	v_mul_f32_e32 v57, v252, v57
	v_mul_f32_e32 v58, v252, v58
	v_mul_f32_e32 v59, v252, v59
	v_cvt_pk_bf16_f32 v204, v56, v57
	v_cvt_pk_bf16_f32 v205, v58, v59
	global_store_dwordx2 v[244:245], v[204:205], off offset:32
	v_mul_f32_e32 v88, v252, v88
	v_mul_f32_e32 v89, v252, v89
	v_mul_f32_e32 v90, v252, v90
	v_mul_f32_e32 v91, v252, v91
	v_cvt_pk_bf16_f32 v210, v88, v89
	v_cvt_pk_bf16_f32 v211, v90, v91
	global_store_dwordx2 v[244:245], v[210:211], off offset:64
	v_mul_f32_e32 v120, v252, v120
	v_mul_f32_e32 v121, v252, v121
	v_mul_f32_e32 v122, v252, v122
	v_mul_f32_e32 v123, v252, v123
	v_cvt_pk_bf16_f32 v212, v120, v121
	v_cvt_pk_bf16_f32 v213, v122, v123
	global_store_dwordx2 v[244:245], v[212:213], off offset:96
	v_add_co_u32_e32 v244, vcc, 0x8000, v244
	s_nop 1
	v_addc_co_u32_e32 v245, vcc, 0, v245, vcc
	v_mul_f32_e32 v28, v253, v28
	v_mul_f32_e32 v29, v253, v29
	v_mul_f32_e32 v30, v253, v30
	v_mul_f32_e32 v31, v253, v31
	v_cvt_pk_bf16_f32 v202, v28, v29
	v_cvt_pk_bf16_f32 v203, v30, v31
	global_store_dwordx2 v[244:245], v[202:203], off offset:0
	v_mul_f32_e32 v60, v253, v60
	v_mul_f32_e32 v61, v253, v61
	v_mul_f32_e32 v62, v253, v62
	v_mul_f32_e32 v63, v253, v63
	v_cvt_pk_bf16_f32 v204, v60, v61
	v_cvt_pk_bf16_f32 v205, v62, v63
	global_store_dwordx2 v[244:245], v[204:205], off offset:32
	v_mul_f32_e32 v92, v253, v92
	v_mul_f32_e32 v93, v253, v93
	v_mul_f32_e32 v94, v253, v94
	v_mul_f32_e32 v95, v253, v95
	v_cvt_pk_bf16_f32 v210, v92, v93
	v_cvt_pk_bf16_f32 v211, v94, v95
	global_store_dwordx2 v[244:245], v[210:211], off offset:64
	v_mul_f32_e32 v124, v253, v124
	v_mul_f32_e32 v125, v253, v125
	v_mul_f32_e32 v126, v253, v126
	v_mul_f32_e32 v127, v253, v127
	v_cvt_pk_bf16_f32 v212, v124, v125
	v_cvt_pk_bf16_f32 v213, v126, v127
	global_store_dwordx2 v[244:245], v[212:213], off offset:96
	s_add_i32 s11, s11, 1
	s_cmp_lt_u32 s11, 4
	s_cbranch_scc1 .Lg3_chunk
	s_mov_b32 s11, 0
	s_add_i32 s10, s10, s95
	s_cmpk_gt_i32 s10, 0x1ff
	s_cbranch_scc1 .Lg3_done
	v_and_b32_e32 v244, 15, v208
	v_lshlrev_b32_e32 v244, 2, v244
	s_lshl_b32 s2, s10, 9
	s_add_i32 s2, s2, 0x36c80000
	v_add_u32_e32 v244, s2, v244
	v_mov_b32_e32 v245, s93
	v_add_co_u32_e32 v244, vcc, s92, v244
	s_nop 1
	v_addc_co_u32_e32 v245, vcc, 0, v245, vcc
	global_load_dword v246, v[244:245], off
	global_load_dword v247, v[244:245], off offset:64
	global_load_dword v248, v[244:245], off offset:128
	global_load_dword v249, v[244:245], off offset:192
	global_load_dword v250, v[244:245], off offset:256
	global_load_dword v251, v[244:245], off offset:320
	global_load_dword v252, v[244:245], off offset:384
	global_load_dword v253, v[244:245], off offset:448
	s_branch .Lg3_chunk
